# mixer_pre stage 0: next item's nine conv-input loads issued right after this item's LDS writes (registers untouched by later stages); conv weights issued before them
# speedup vs baseline: 1.0139x; 1.0029x over previous
; #define LAS __attribute__((address_space(3)))
; __device__ __forceinline__ void mixer_pre_item(int item, const float* const* in, int l, unsigned char* ws, LAS unsigned char* lds, int tid, int lane, int wave) {
;     ...
;     __syncthreads();
; #pragma unroll
;     for (int i = 0; i < 9; ++i) { const int id = tid + 512 * i;
;         if (id < 35 * 128) { const int row = id >> 7, pc = id & 127, s = s0 - 3 + row;
;             u32x4v v = (u32x4v){0u, 0u, 0u, 0u};
;             if (s >= 0) v = *(const u32x4v*)(U + ((size_t)b * SEQ + s) * NIN + (pc < 32 ? pc * 8 : U_DQ + (pc - 32) * 8));
;             if (pc < 32) *(LAS u32x4v*)(STGL + row * 256 + pc * 8) = v; else *(LAS u32x4v*)(STGD + row * 768 + (pc - 32) * 8) = v; } }
.LBB0_567:
	v_mov_b32_e32 v34, v166
	s_ashr_i32 s18, s14, 6
	v_and_b32_e32 v2, 0x7f, v34
	v_lshlrev_b32_e32 v0, 3, v2
	v_or_b32_e32 v3, 0x400, v0
	v_cmp_gt_u32_e64 s[40:41], 32, v2
	s_lshl_b32 s9, s14, 5
	v_readlane_b32 s34, v251, 4
	v_cndmask_b32_e64 v0, v3, v0, s[40:41]
	s_and_b32 s30, s9, 0x7e0
	s_ashr_i32 s19, s18, 31
	v_lshlrev_b32_e32 v0, 1, v0
	v_readlane_b32 s35, v251, 5
	s_movk_i32 s31, 0x1180
	v_readfirstlane_b32 s15, v34
	s_lshl_b64 s[20:21], s[18:19], 11
	s_add_i32 s9, s30, -3
	v_cmp_lt_u32_e32 vcc, 31, v2
	v_lshl_add_u64 v[8:9], s[34:35], 0, v[0:1]
	v_lshl_add_u32 v6, v2, 4, 0
	v_cmp_gt_i32_e64 s[40:41], s31, v34
	s_barrier
	v_ashrrev_i32_e32 v7, 7, v34
	v_readlane_b32 s31, v248, 16
	s_cmp_eq_u32 s14, s31
	s_cbranch_scc0 .Lp_have
	v_add_u32_e32 v0, s9, v7
	v_mov_b32_e32 v80, 0
	v_mov_b32_e32 v81, 0
	v_mov_b32_e32 v82, 0
	v_mov_b32_e32 v83, 0
	v_cmp_lt_i32_e64 s[38:39], -1, v0
	s_and_saveexec_b64 s[42:43], s[38:39]
	v_lshl_add_u64 v[2:3], s[20:21], 0, v[0:1]
	v_mad_u64_u32 v[4:5], s[34:35], v2, s36, v[8:9]
	v_mad_i32_i24 v5, v3, s36, v5
	global_load_dwordx4 v[80:83], v[4:5], off
	s_or_b64 exec, exec, s[42:43]
	v_add_u32_e32 v0, 4, v0
	v_lshl_add_u64 v[2:3], s[20:21], 0, v[0:1]
	v_mad_u64_u32 v[4:5], s[34:35], v2, s36, v[8:9]
	v_mad_i32_i24 v5, v3, s36, v5
	s_mov_b64 s[42:43], 0x5000
	global_load_dwordx4 v[84:87], v[4:5], off
	v_lshl_add_u64 v[4:5], v[4:5], 0, s[42:43]
	global_load_dwordx4 v[88:91], v[4:5], off
	v_lshl_add_u64 v[4:5], v[4:5], 0, s[42:43]
	global_load_dwordx4 v[92:95], v[4:5], off
	v_lshl_add_u64 v[4:5], v[4:5], 0, s[42:43]
	global_load_dwordx4 v[96:99], v[4:5], off
	v_lshl_add_u64 v[4:5], v[4:5], 0, s[42:43]
	global_load_dwordx4 v[100:103], v[4:5], off
	v_lshl_add_u64 v[4:5], v[4:5], 0, s[42:43]
	global_load_dwordx4 v[104:107], v[4:5], off
	v_lshl_add_u64 v[4:5], v[4:5], 0, s[42:43]
	global_load_dwordx4 v[184:187], v[4:5], off
	v_lshl_add_u64 v[4:5], v[4:5], 0, s[42:43]
	s_movk_i32 s31, 0x180
	v_cmp_gt_i32_e64 s[40:41], s31, v34
	s_and_saveexec_b64 s[38:39], s[40:41]
	global_load_dwordx4 v[188:191], v[4:5], off
	s_or_b64 exec, exec, s[38:39]
; #define LAS __attribute__((address_space(3)))
; __device__ __forceinline__ void mixer_pre_item(int item, const float* const* in, int l, unsigned char* ws, LAS unsigned char* lds, int tid, int lane, int wave) {
;     ...
;     __syncthreads();
; #pragma unroll
;     for (int i = 0; i < 9; ++i) { const int id = tid + 512 * i;
;         if (id < 35 * 128) { const int row = id >> 7, pc = id & 127, s = s0 - 3 + row;
;             u32x4v v = (u32x4v){0u, 0u, 0u, 0u};
;             if (s >= 0) v = *(const u32x4v*)(U + ((size_t)b * SEQ + s) * NIN + (pc < 32 ? pc * 8 : U_DQ + (pc - 32) * 8));
;             if (pc < 32) *(LAS u32x4v*)(STGL + row * 256 + pc * 8) = v; else *(LAS u32x4v*)(STGD + row * 768 + (pc - 32) * 8) = v; } }
;     __syncthreads();
;     for (int task = wave; task < 24; task += 8) {
;         const int g = task >> 1, t0 = (task & 1) * 16, kind = g >> 2, hh = g & 3, cc = g * 64 + lane;
;         const float* cw = in[17] + (size_t)l * 4 * 768;
;         const float w0 = cw[cc], w1 = cw[768 + cc], w2 = cw[1536 + cc], w3 = cw[2304 + cc];
.Lp_have:
	v_lshl_add_u32 v10, v7, 9, v6
	s_movk_i32 s31, 0x600
	v_mad_u32_u24 v11, v7, s31, v6
	v_add_u32_e32 v11, 0x4400, v11
	v_mov_b32_e32 v2, 0x800
	v_mov_b32_e32 v3, 0x1800
	v_cndmask_b32_e32 v10, v10, v11, vcc
	v_cndmask_b32_e32 v11, v2, v3, vcc
	s_waitcnt vmcnt(0)
	ds_write_b128 v10, v[80:83]
	v_add_u32_e32 v10, v10, v11
	ds_write_b128 v10, v[84:87]
	v_add_u32_e32 v10, v10, v11
	ds_write_b128 v10, v[88:91]
	v_add_u32_e32 v10, v10, v11
	ds_write_b128 v10, v[92:95]
	v_add_u32_e32 v10, v10, v11
	ds_write_b128 v10, v[96:99]
	v_add_u32_e32 v10, v10, v11
	ds_write_b128 v10, v[100:103]
	v_add_u32_e32 v10, v10, v11
	ds_write_b128 v10, v[104:107]
	v_add_u32_e32 v10, v10, v11
	ds_write_b128 v10, v[184:187]
	v_add_u32_e32 v10, v10, v11
	s_movk_i32 s31, 0x180
	v_cmp_gt_i32_e64 s[40:41], s31, v34
	s_and_saveexec_b64 s[38:39], s[40:41]
	ds_write_b128 v10, v[188:191]
	s_or_b64 exec, exec, s[38:39]
	s_ashr_i32 s100, s15, 6
	s_lshl_b32 s100, s100, 5
	s_andn2_b32 s100, s100, 63
	v_and_b32_e32 v146, 63, v34
	v_or_b32_e32 v144, s100, v146
	v_ashrrev_i32_e32 v145, 31, v144
	v_lshl_add_u64 v[144:145], v[144:145], 2, s[10:11]
	s_mov_b64 s[100:101], 0x400
	global_load_dword v148, v[144:145], off
	global_load_dword v149, v[144:145], off offset:3072
	v_add_co_u32_e64 v146, s[38:39], s37, v144
	s_nop 1
	v_addc_co_u32_e64 v147, s[38:39], 0, v145, s[38:39]
	global_load_dword v150, v[146:147], off offset:2048
	v_add_co_u32_e64 v146, s[38:39], s77, v144
	s_nop 1
	v_addc_co_u32_e64 v147, s[38:39], 0, v145, s[38:39]
	global_load_dword v151, v[146:147], off offset:1024
	v_lshl_add_u64 v[144:145], v[144:145], 0, s[100:101]
	global_load_dword v152, v[144:145], off
	global_load_dword v153, v[144:145], off offset:3072
	v_add_co_u32_e64 v146, s[38:39], s37, v144
	s_nop 1
	v_addc_co_u32_e64 v147, s[38:39], 0, v145, s[38:39]
	global_load_dword v154, v[146:147], off offset:2048
	v_add_co_u32_e64 v146, s[38:39], s77, v144
	s_nop 1
	v_addc_co_u32_e64 v147, s[38:39], 0, v145, s[38:39]
	global_load_dword v155, v[146:147], off offset:1024
	v_lshl_add_u64 v[144:145], v[144:145], 0, s[100:101]
	global_load_dword v168, v[144:145], off
	global_load_dword v169, v[144:145], off offset:3072
	v_add_co_u32_e64 v146, s[38:39], s37, v144
	s_nop 1
	v_addc_co_u32_e64 v147, s[38:39], 0, v145, s[38:39]
	global_load_dword v170, v[146:147], off offset:2048
	v_add_co_u32_e64 v146, s[38:39], s77, v144
	s_nop 1
	v_addc_co_u32_e64 v147, s[38:39], 0, v145, s[38:39]
	global_load_dword v171, v[146:147], off offset:1024
	s_add_i32 s31, s14, s72
	s_cmpk_gt_i32 s31, 0x3ff
	s_cbranch_scc1 .Lp_none
	s_ashr_i32 s100, s31, 6
	s_ashr_i32 s101, s100, 31
	s_lshl_b64 s[100:101], s[100:101], 11
	s_lshl_b32 s31, s31, 5
	s_and_b32 s31, s31, 0x7e0
	s_add_i32 s31, s31, -3
	v_add_u32_e32 v0, s31, v7
	v_mov_b32_e32 v80, 0
	v_mov_b32_e32 v81, 0
	v_mov_b32_e32 v82, 0
	v_mov_b32_e32 v83, 0
	v_cmp_lt_i32_e64 s[38:39], -1, v0
	s_and_saveexec_b64 s[42:43], s[38:39]
	v_lshl_add_u64 v[2:3], s[100:101], 0, v[0:1]
	v_mad_u64_u32 v[4:5], s[34:35], v2, s36, v[8:9]
	v_mad_i32_i24 v5, v3, s36, v5
	global_load_dwordx4 v[80:83], v[4:5], off
	s_or_b64 exec, exec, s[42:43]
	v_add_u32_e32 v0, 4, v0
	v_lshl_add_u64 v[2:3], s[100:101], 0, v[0:1]
	v_mad_u64_u32 v[4:5], s[34:35], v2, s36, v[8:9]
	v_mad_i32_i24 v5, v3, s36, v5
	s_mov_b64 s[42:43], 0x5000
	global_load_dwordx4 v[84:87], v[4:5], off
	v_lshl_add_u64 v[4:5], v[4:5], 0, s[42:43]
	global_load_dwordx4 v[88:91], v[4:5], off
	v_lshl_add_u64 v[4:5], v[4:5], 0, s[42:43]
	global_load_dwordx4 v[92:95], v[4:5], off
	v_lshl_add_u64 v[4:5], v[4:5], 0, s[42:43]
	global_load_dwordx4 v[96:99], v[4:5], off
	v_lshl_add_u64 v[4:5], v[4:5], 0, s[42:43]
	global_load_dwordx4 v[100:103], v[4:5], off
	v_lshl_add_u64 v[4:5], v[4:5], 0, s[42:43]
	global_load_dwordx4 v[104:107], v[4:5], off
	v_lshl_add_u64 v[4:5], v[4:5], 0, s[42:43]
	global_load_dwordx4 v[184:187], v[4:5], off
	v_lshl_add_u64 v[4:5], v[4:5], 0, s[42:43]
	s_movk_i32 s31, 0x180
	v_cmp_gt_i32_e64 s[40:41], s31, v34
	s_and_saveexec_b64 s[38:39], s[40:41]
	global_load_dwordx4 v[188:191], v[4:5], off
	s_or_b64 exec, exec, s[38:39]
.Lp_none:
	s_bfe_u32 s9, s8, 0x60005
	s_ashr_i32 s31, s15, 6
	v_and_b32_e32 v35, 63, v34
	s_cmp_lt_i32 s31, 24
	s_waitcnt lgkmcnt(0)
	s_barrier
	s_cbranch_scc0 .LBB0_633
	v_lshlrev_b32_e32 v0, 1, v35
	v_readlane_b32 s33, v248, 48
	s_lshl_b32 s35, s9, 5
	s_lshl_b32 s34, s31, 5
	v_add_u32_e32 v18, s33, v0
	s_lshl_b32 s33, s31, 4
	v_readlane_b32 s38, v249, 59
	v_readlane_b32 s39, v249, 60
	s_add_u32 s35, s20, s35
	s_addc_u32 s42, s21, 0
	v_lshl_add_u64 v[2:3], s[38:39], 0, v[0:1]
	s_add_i32 s100, s14, s72
	s_cmpk_gt_i32 s100, 0x3ff
	s_cbranch_scc1 .Lcw_last
	s_waitcnt vmcnt(17)
	s_branch .Lcw_go
.Lcw_last:
	s_waitcnt vmcnt(8)
.Lcw_go:
	s_branch .LBB0_615
.LBB0_614:
	s_waitcnt vmcnt(16)
	v_mov_b32_e32 v148, v152
	v_mov_b32_e32 v149, v153
	v_mov_b32_e32 v150, v154
	v_mov_b32_e32 v151, v155
	v_mov_b32_e32 v152, v168
	v_mov_b32_e32 v153, v169
	v_mov_b32_e32 v154, v170
	v_mov_b32_e32 v155, v171
	s_add_i32 s38, s31, 8
	s_addk_i32 s33, 0x80
	s_addk_i32 s34, 0x100
	s_cmp_gt_i32 s31, 15
	s_mov_b32 s31, s38
	s_cbranch_scc1 .LBB0_633
